# sp1: logical wave ids permuted so the 1024 two-item waves are spread over all workgroups
# baseline (speedup 1.0000x reference)
; #define LAS __attribute__((address_space(3)))
; __device__ __forceinline__ void retout_item(const bf16_t* hbuf, const float* rot, const float* kvbuf, const float* normg, bf16_t* mixed, LAS bf16_t* vT, int item, int lane) {
;     const int bh = item / NCHUNK, n = item % NCHUNK, b = bh / 6, h = bh % 6; const size_t t0 = (size_t)b * SEQ + (size_t)n * 64;
;     const int r = lane & 15, q = lane >> 4; const float l2g = log2_gamma(h);
;     load_tile_T<false>(hbuf + t0 * INWP + C_RV + h * 64, vT, lane, 0.f, 0.f);
;     const float* cs = rot; const float* sn = rot + 16384 * 32;
;     bf16x8 kf[4][2]; LAS bf16_t* RT = vT + 64 * TLD;
; #pragma unroll
;     for (int mt = 0; mt < 4; ++mt) { const int row = 16 * mt + r; const bf16_t* kp = hbuf + (t0 + row) * INWP + C_RK + h * 64 + 8 * q; const int pos = n * 64 + row; u32x4 o1, o2;
;         rot8(*(const u32x4*)kp, *(const u32x4*)(kp + 32), cs + (size_t)pos * 32 + 8 * q, sn + (size_t)pos * 32 + 8 * q, 0.125f, o1, o2); kf[mt][0] = as_bf16x8(o1); kf[mt][1] = as_bf16x8(o2); }
; __device__ __forceinline__ void run_phase(const Args& a, const int ph, LAS unsigned char* lds, const int tid, const int rpt) {
;     const int lane = tid & 63, wave = __builtin_amdgcn_readfirstlane(tid >> 6), G = gridDim.x;
;     const int gw = blockIdx.x * 8 + wave, NGW = G * 8;
;     unsigned char* ws = a.ws;
;     bf16_t* hbuf = (bf16_t*)(ws + WS_HBUF); bf16_t* mixed = (bf16_t*)(ws + WS_MIXED); float* kvbuf = (float*)(ws + WS_KV);
;     const float* rot = (const float*)(ws + WS_ROT);
;     LAS int* TAB = (LAS int*)(lds + TAB_OFF);
;     {
;         if (ph == 0) { phase_prologue(a, lds, tid); }
;         else {
;             const int l = (ph - 1) / 10, sp = (ph - 1) % 10;
;             int* cnt = (int*)(ws + WS_CTL) + l * 32; float* kmax2 = (float*)(ws + WS_CTL + 1024) + l * 12;
;             if (sp == 0) {
;                 pg8::DenseOrder S; S.init(ws + WS_XB, ws + WS_WIN + (size_t)l * INWP * 1024 * 2, NTOK, INWP, 1024, G, blockIdx.x);
;                 pg8::EpiBf16Bias E{hbuf, INWP, (const float*)(ws + WS_BPAD) + l * INWP};
;                 pg8::gemm_phase<false, false>(lds, tid, 1024, S, E);
;             } else if (sp == 1) {
;                 for (int it = gw; it < (NTOK / 16) * 4; it += NGW) pool_item(hbuf, (const bf16_t*)(ws + WS_POOLW) + l * 4 * 4096, a.in[4] + l * 256, mixed, it, lane);
.LBB0_170:
	s_ashr_i32 s15, s71, 6
	v_readlane_b32 s12, v251, 16
	s_add_i32 s16, s15, s12
	v_readlane_b32 s98, v254, 48
	s_lshr_b32 s99, s12, 1
	s_and_b32 s100, s15, 3
	s_add_i32 s99, s99, s100
	s_lshr_b32 s100, s15, 2
	s_lshl_b32 s100, s100, 10
	s_add_i32 s99, s99, s100
	s_cmp_eq_u32 s98, 1
	s_cselect_b32 s16, s99, s16
	s_and_b64 vcc, exec, s[0:1]
	v_writelane_b32 v249, s15, 52
	s_cbranch_vccz .LBB0_352
	v_readlane_b32 s0, v254, 48
	s_cmp_gt_i32 s0, 1
	s_mov_b64 s[0:1], -1
	s_cbranch_scc0 .LBB0_322
	v_readlane_b32 s0, v254, 48
	s_cmp_gt_i32 s0, 2
	s_mov_b64 s[0:1], -1
	s_cbranch_scc0 .LBB0_179
	s_cmpk_gt_i32 s16, 0xbff
	s_cbranch_scc1 .LBB0_178
	v_lshrrev_b32_e32 v1, 4, v248
	v_readlane_b32 s20, v251, 19
	v_lshlrev_b32_e32 v32, 5, v1
	v_readlane_b32 s21, v251, 20
	v_readlane_b32 s0, v249, 52
	s_mulk_i32 s0, 0x4800
	s_waitcnt vmcnt(0)
	v_lshl_add_u64 v[64:65], s[20:21], 0, v[32:33]
	v_readlane_b32 s20, v251, 59
	v_readlane_b32 s21, v251, 60
	v_lshrrev_b32_e32 v3, 3, v248
	v_and_b32_e32 v4, 7, v168
	v_lshl_add_u64 v[66:67], s[20:21], 0, v[32:33]
	v_readlane_b32 s20, v251, 57
	v_readlane_b32 s21, v251, 58
	s_add_i32 s0, s0, 0
	v_lshlrev_b32_e32 v0, 3, v4
	v_mul_u32_u24_e32 v2, 0xc00, v3
	v_mul_u32_u24_e32 v4, 0x480, v4
	v_lshlrev_b32_e32 v3, 1, v3
	v_lshlrev_b32_e32 v62, 3, v1
	v_lshl_add_u64 v[74:75], s[20:21], 0, v[32:33]
	v_and_b32_e32 v32, 48, v248
	v_lshlrev_b32_e32 v61, 2, v1
	v_lshlrev_b32_e32 v1, 2, v248
	v_and_b32_e32 v60, 15, v168
	v_add3_u32 v39, s0, v4, v3
	v_or_b32_e32 v72, 48, v248
	v_add_u32_e32 v3, s0, v32
	v_xor_b32_e32 v69, 64, v1
	v_xor_b32_e32 v71, 0x80, v1
	v_mov_b32_e32 v1, s0
	s_movk_i32 s0, 0x90
	v_mad_u32_u24 v73, v60, s0, v1
	v_mad_u32_u24 v109, v72, s0, v1
	v_readlane_b32 s0, v249, 5
	v_readlane_b32 s1, v249, 6
	v_mov_b32_e32 v63, v33
	v_or_b32_e32 v68, 16, v60
	v_lshl_add_u64 v[76:77], s[0:1], 0, v[32:33]
	v_readlane_b32 s0, v253, 38
	v_readlane_b32 s1, v253, 39
	v_or_b32_e32 v70, 32, v60
	v_add_u32_e32 v105, 0x900, v73
	v_add_u32_e32 v107, 0x1200, v73
	v_lshl_add_u64 v[78:79], s[0:1], 0, v[62:63]
	v_readlane_b32 s44, v251, 0
	v_readlane_b32 s0, v253, 40
	v_lshlrev_b32_e32 v4, 6, v60
	v_mul_u32_u24_e32 v5, 0x90, v60
	v_lshlrev_b32_e32 v6, 6, v68
	v_lshlrev_b32_e32 v8, 6, v70
	v_lshlrev_b32_e32 v10, 6, v72
	v_mul_u32_u24_e32 v7, 0x90, v72
	v_add_u32_e32 v104, v73, v32
	v_add_u32_e32 v106, v105, v32
	v_add_u32_e32 v108, v107, v32
	v_add_u32_e32 v110, v109, v32
	v_sub_u32_e32 v1, v61, v60
	v_and_b32_e32 v32, 48, v168
	v_readlane_b32 s50, v251, 6
	v_readlane_b32 s51, v251, 7
	v_readlane_b32 s1, v253, 41
	v_or_b32_e32 v111, 1, v61
	v_or_b32_e32 v112, 2, v61
	v_or_b32_e32 v113, 3, v61
	v_or_b32_e32 v114, 16, v61
	v_or_b32_e32 v115, 17, v61
	v_or_b32_e32 v116, 18, v61
	v_or_b32_e32 v117, 19, v61
	v_or_b32_e32 v118, 32, v61
	v_or_b32_e32 v119, 33, v61
	v_or_b32_e32 v120, 34, v61
	v_or_b32_e32 v121, 35, v61
	v_or_b32_e32 v122, 48, v61
	v_or_b32_e32 v123, 49, v61
	v_or_b32_e32 v124, 50, v61
	v_or_b32_e32 v125, 51, v61
	v_add_u32_e32 v126, 51, v1
	v_sub_u32_e32 v127, v60, v61
	v_lshl_add_u64 v[80:81], s[50:51], 0, v[32:33]
	v_lshl_add_u64 v[82:83], s[0:1], 0, v[62:63]
	v_lshlrev_b32_e32 v32, 1, v0
	v_lshlrev_b32_e32 v84, 1, v2
	v_lshlrev_b32_e32 v86, 1, v62
	v_lshlrev_b32_e32 v88, 2, v4
	v_add_u32_e32 v63, v3, v5
	v_lshlrev_b32_e32 v90, 2, v6
	v_lshlrev_b32_e32 v92, 2, v8
	v_lshlrev_b32_e32 v94, 2, v10
	v_add_u32_e32 v128, v3, v7
	s_mov_b32 s0, s16
	v_readlane_b32 s45, v251, 1
	v_readlane_b32 s46, v251, 2
	v_readlane_b32 s47, v251, 3
	v_readlane_b32 s48, v251, 4
	v_readlane_b32 s49, v251, 5
